# comb4 + rstd of the first FFN-in unit precomputed at the phase preheader (no 16-load path left in steady state)
# speedup vs baseline: 1.0319x; 1.0077x over previous
; #define PG8_STAGE(bufoff, gbase, voff) do { _Pragma("unroll") for (int _i = 0; _i < 2; ++_i) \
;         __builtin_amdgcn_global_load_lds((const unsigned*)((const char*)(gbase) + (voff)[_i]), (LAS unsigned*)(lds + (bufoff) + ldsw + _i * 8192), 16, 0, 0); } while (0)
; #define PG8_WAIT_V(n) asm volatile("s_waitcnt vmcnt(" #n ")" ::: "memory")
; #define PG8_BAR __builtin_amdgcn_s_barrier()
; __device__ __forceinline__ void load_rstd(const float* part, int row0, int fq, float (&rs)[2][4]) {
;     ...
;         for (int m = 0; m < 4; ++m) { const float* p = part + (size_t)(row0 + ai * HALF + m * 16) * NPART + fq * 8;
;             const f32x4 a = *(const f32x4*)p, b = *(const f32x4*)(p + 4); float s = ((a[0] + a[1]) + (a[2] + a[3])) + ((b[0] + b[1]) + (b[2] + b[3]));
;             s += __shfl_xor(s, 16); s += __shfl_xor(s, 32); rs[ai][m] = rsqrtf(s * (1.0f / D) + RMS_EPS); }
; template <class Epi, class Sched, bool ALIGN_EPI>
; __device__ __forceinline__ void gemm_phase(LAS unsigned char* lds, const Gemm g, const Sched& S, const Epi& E) {
;     ...
;     const char* cA = (const char*)g.A + (size_t)cur.aoff * 2; const char* cB = (const char*)g.Bt + (size_t)cur.boff * 2;
;     PG8_STAGE(PG8_SB(0, 0), cB, voffB); PG8_STAGE(PG8_SB(0, 1), cB + hB, voffB); PG8_STAGE(PG8_SA(0, 0), cA, voffA); PG8_STAGE(PG8_SA(0, 1), cA + hA, voffA);
;     if (wr == 1) PG8_BAR;
;     PG8_WAIT_V(2); PG8_BAR;
;     PG8_STAGE(PG8_SB(1, 0), cB + kstep, voffB); PG8_STAGE(PG8_SA(1, 0), cA + kstep, voffA); PG8_STAGE(PG8_SB(1, 1), cB + hB + kstep, voffB);
;     PG8_WAIT_V(6); PG8_BAR;
.LBB0_255:
	s_lshl_b32 s19, s36, 5
	s_mov_b64 s[36:37], 0x80
	s_add_i32 m0, s70, 0x18000
	v_lshl_add_u64 v[6:7], v[6:7], 0, s[36:37]
	s_lshl_b32 s18, s3, 13
	s_and_b32 s19, s19, 0x60
	s_waitcnt vmcnt(2)
	s_barrier
	global_load_lds_dwordx4 v[6:7], off
	v_lshl_add_u64 v[4:5], v[4:5], 0, s[36:37]
	s_add_i32 m0, s70, 0x1a000
	s_add_i32 s78, s70, 0x8000
	s_add_i32 s79, s70, 0xa000
	global_load_lds_dwordx4 v[4:5], off
	v_lshl_add_u64 v[0:1], v[0:1], 0, s[36:37]
	s_mov_b32 m0, s78
	s_add_u32 s38, s6, 0x80080
	global_load_lds_dwordx4 v[0:1], off
	v_lshl_add_u64 v[0:1], v[2:3], 0, s[36:37]
	s_mov_b32 m0, s79
	s_addc_u32 s39, s7, 0
	global_load_lds_dwordx4 v[0:1], off
	s_add_i32 m0, s70, 0x1c000
	v_lshl_add_u64 v[0:1], s[38:39], 0, v[144:145]
	global_load_lds_dwordx4 v[0:1], off
	v_lshl_add_u64 v[0:1], s[38:39], 0, v[146:147]
	s_add_i32 m0, s70, 0x1e000
	s_cmpk_lt_u32 s2, 0x100
	global_load_lds_dwordx4 v[0:1], off
	v_lshlrev_b32_e32 v1, 2, v182
	v_lshl_or_b32 v0, v182, 6, v183
	v_and_b32_e32 v1, 32, v1
	v_bitop3_b32 v2, v0, s18, v1 bitop3:0xde
	v_lshlrev_b32_e32 v0, 2, v181
	v_mov_b32_e32 v1, v145
	v_lshl_add_u64 v[152:153], s[48:49], 0, v[0:1]
	v_lshlrev_b32_e32 v0, 9, v221
	v_and_b32_e32 v0, 0x70000, v0
	v_lshlrev_b32_e32 v1, 12, v187
	v_or3_b32 v0, v185, v0, v1
	v_add_u32_e32 v154, v0, v186
	v_lshlrev_b32_e32 v0, 5, v188
	v_and_b32_e32 v0, 0xf0000, v0
	s_waitcnt vmcnt(6)
	v_or3_b32 v0, v185, v0, v1
	v_lshl_or_b32 v193, s19, 7, v184
	s_cselect_b64 s[38:39], -1, 0
	v_add_u32_e32 v156, v0, v186
	s_add_i32 s82, 0, 0x10000
	s_add_i32 s83, 0, 0x14000
	v_mbcnt_lo_u32_b32 v0, -1, 0
	v_lshl_or_b32 v192, s3, 6, v182
	s_ashr_i32 s80, s34, 31
	s_mov_b32 s81, s34
	v_or_b32_e32 v194, s19, v181
	v_mov_b32_e32 v155, v145
	v_mov_b32_e32 v157, v145
	v_mov_b64_e32 v[158:159], 0x580
	v_mov_b64_e32 v[160:161], 0x57f
	v_add_u32_e32 v195, s82, v193
	v_add_u32_e32 v196, s83, v193
	v_add_u32_e32 v197, 0, v2
	v_mbcnt_hi_u32_b32 v198, -1, v0
	s_mov_b32 s40, 0x3a000000
	s_mov_b32 s84, 0x800000
	s_movk_i32 s88, 0x2c00
	s_mov_b32 s89, 0
	s_barrier
	v_lshrrev_b32_e32 v216, 1, v220
	s_lshl_b32 s96, s11, 8
	s_lshl_b32 s97, s95, 5
	s_add_i32 s96, s96, s97
	v_add_u32_e32 v216, s96, v216
	v_and_b32_e32 v217, 1, v220
	v_lshlrev_b32_e32 v217, 6, v217
	v_lshl_add_u32 v216, v216, 7, v217
	s_add_u32 s96, s14, 0xc300000
	s_addc_u32 s97, s15, 0
	global_load_dwordx4 v[200:203], v216, s[96:97]
	global_load_dwordx4 v[204:207], v216, s[96:97] offset:16
	global_load_dwordx4 v[208:211], v216, s[96:97] offset:32
	global_load_dwordx4 v[212:215], v216, s[96:97] offset:48
	v_mov_b32_e32 v217, 0x358637bd
	s_waitcnt vmcnt(0)
	v_add_f32_e32 v200, v200, v201
	v_add_f32_e32 v202, v202, v203
	v_add_f32_e32 v204, v204, v205
	v_add_f32_e32 v206, v206, v207
	v_add_f32_e32 v208, v208, v209
	v_add_f32_e32 v210, v210, v211
	v_add_f32_e32 v212, v212, v213
	v_add_f32_e32 v214, v214, v215
	v_add_f32_e32 v200, v200, v202
	v_add_f32_e32 v204, v204, v206
	v_add_f32_e32 v208, v208, v210
	v_add_f32_e32 v212, v212, v214
	v_add_f32_e32 v200, v200, v204
	v_add_f32_e32 v208, v208, v212
	v_add_f32_e32 v200, v200, v208
	s_nop 1
	v_add_f32_dpp v204, v200, v200 quad_perm:[1,0,3,2] row_mask:0xf bank_mask:0xf
	v_fmamk_f32 v204, v204, 0x3a000000, v217
	v_rsq_f32_e32 v204, v204
	s_lshl_b32 s96, s95, 7
	s_add_i32 s96, s96, 0x21000
	v_lshrrev_b32_e32 v216, 1, v220
	v_lshl_add_u32 v216, v216, 2, s96
	ds_write_b32 v216, v204
	s_mov_b32 s99, 2
	s_branch .LBB0_258

; #define PG8_STAGE(bufoff, gbase, voff) do { _Pragma("unroll") for (int _i = 0; _i < 2; ++_i) \
;         __builtin_amdgcn_global_load_lds((const unsigned*)((const char*)(gbase) + (voff)[_i]), (LAS unsigned*)(lds + (bufoff) + ldsw + _i * 8192), 16, 0, 0); } while (0)
; #define PG8_WAIT_V(n) asm volatile("s_waitcnt vmcnt(" #n ")" ::: "memory")
; #define PG8_BAR __builtin_amdgcn_s_barrier()
; __device__ __forceinline__ void load_rstd(const float* part, int row0, int fq, float (&rs)[2][4]) {
;     ...
;         for (int m = 0; m < 4; ++m) { const float* p = part + (size_t)(row0 + ai * HALF + m * 16) * NPART + fq * 8;
;             const f32x4 a = *(const f32x4*)p, b = *(const f32x4*)(p + 4); float s = ((a[0] + a[1]) + (a[2] + a[3])) + ((b[0] + b[1]) + (b[2] + b[3]));
;             s += __shfl_xor(s, 16); s += __shfl_xor(s, 32); rs[ai][m] = rsqrtf(s * (1.0f / D) + RMS_EPS); }
; template <class Epi, class Sched, bool ALIGN_EPI>
; __device__ __forceinline__ void gemm_phase(LAS unsigned char* lds, const Gemm g, const Sched& S, const Epi& E) {
;     ...
;     const char* cA = (const char*)g.A + (size_t)cur.aoff * 2; const char* cB = (const char*)g.Bt + (size_t)cur.boff * 2;
;     PG8_STAGE(PG8_SB(0, 0), cB, voffB); PG8_STAGE(PG8_SB(0, 1), cB + hB, voffB); PG8_STAGE(PG8_SA(0, 0), cA, voffA); PG8_STAGE(PG8_SA(0, 1), cA + hA, voffA);
;     if (wr == 1) PG8_BAR;
;     PG8_WAIT_V(2); PG8_BAR;
;     PG8_STAGE(PG8_SB(1, 0), cB + kstep, voffB); PG8_STAGE(PG8_SA(1, 0), cA + kstep, voffA); PG8_STAGE(PG8_SB(1, 1), cB + hB + kstep, voffB);
;     PG8_WAIT_V(6); PG8_BAR;
.LBB0_1142:
	s_lshl_b32 s18, s26, 5
	s_mov_b64 s[26:27], 0x80
	s_and_b32 s33, s18, 0x60
	s_add_i32 m0, s58, 0x18000
	v_lshl_add_u64 v[6:7], v[6:7], 0, s[26:27]
	s_lshl_b32 s22, s3, 13
	s_lshl_b32 s30, s33, 7
	s_waitcnt vmcnt(2)
	s_barrier
	global_load_lds_dwordx4 v[6:7], off
	v_lshl_add_u64 v[4:5], v[4:5], 0, s[26:27]
	s_add_i32 m0, s58, 0x1a000
	s_add_i32 s62, s58, 0x8000
	s_add_i32 s63, s58, 0xa000
	global_load_lds_dwordx4 v[4:5], off
	v_lshl_add_u64 v[0:1], v[0:1], 0, s[26:27]
	s_mov_b32 m0, s62
	s_add_u32 s18, s6, 0x80080
	global_load_lds_dwordx4 v[0:1], off
	v_lshl_add_u64 v[0:1], v[2:3], 0, s[26:27]
	s_mov_b32 m0, s63
	s_addc_u32 s19, s7, 0
	global_load_lds_dwordx4 v[0:1], off
	s_add_i32 m0, s58, 0x1c000
	v_lshl_add_u64 v[0:1], s[18:19], 0, v[148:149]
	global_load_lds_dwordx4 v[0:1], off
	v_lshl_add_u64 v[0:1], s[18:19], 0, v[144:145]
	s_add_i32 m0, s58, 0x1e000
	v_and_b32_e32 v2, 32, v180
	global_load_lds_dwordx4 v[0:1], off
	v_and_b32_e32 v0, 15, v221
	v_lshlrev_b32_e32 v1, 1, v11
	v_lshl_or_b32 v181, s3, 6, v0
	v_lshl_or_b32 v0, v0, 6, v1
	v_bitop3_b32 v3, v0, s22, v2 bitop3:0xde
	v_lshlrev_b32_e32 v0, 6, v221
	s_movk_i32 s3, 0x3c0
	v_and_or_b32 v0, v0, s3, v1
	v_bitop3_b32 v182, s30, v0, v2 bitop3:0xf6
	v_lshlrev_b32_e32 v0, 2, v11
	v_mov_b32_e32 v1, v149
	v_lshl_add_u64 v[152:153], s[48:49], 0, v[0:1]
	v_lshlrev_b32_e32 v0, 9, v221
	v_and_b32_e32 v0, 0x70000, v0
	v_lshlrev_b32_e32 v1, 12, v12
	v_or3_b32 v0, v9, v0, v1
	v_add_u32_e32 v154, v0, v10
	v_lshlrev_b32_e32 v0, 5, v8
	v_and_b32_e32 v0, 0xf0000, v0
	s_waitcnt vmcnt(6)
	s_cmpk_lt_u32 s2, 0x100
	v_or3_b32 v0, v9, v0, v1
	s_cselect_b64 s[30:31], -1, 0
	v_add_u32_e32 v156, v0, v10
	s_add_i32 s66, 0, 0x10000
	s_add_i32 s67, 0, 0x14000
	v_mbcnt_lo_u32_b32 v0, -1, 0
	s_ashr_i32 s64, s34, 31
	s_mov_b32 s65, s34
	v_or_b32_e32 v183, s33, v11
	v_mov_b32_e32 v155, v149
	v_mov_b32_e32 v157, v149
	v_mov_b64_e32 v[158:159], 0x580
	v_mov_b64_e32 v[160:161], 0x57f
	v_add_u32_e32 v184, s66, v182
	v_add_u32_e32 v185, s67, v182
	v_add_u32_e32 v186, 0, v3
	v_mbcnt_hi_u32_b32 v187, -1, v0
	s_mov_b32 s36, 0x3a000000
	s_mov_b32 s38, 0x358637bd
	s_mov_b32 s68, 0x800000
	s_movk_i32 s69, 0x2c00
	s_mov_b32 s70, 0
	s_barrier
	v_lshrrev_b32_e32 v204, 1, v220
	s_lshl_b32 s96, s11, 8
	s_lshl_b32 s97, s95, 5
	s_add_i32 s96, s96, s97
	v_add_u32_e32 v204, s96, v204
	v_and_b32_e32 v205, 1, v220
	v_lshlrev_b32_e32 v205, 6, v205
	v_lshl_add_u32 v204, v204, 7, v205
	s_add_u32 s96, s14, 0xc300000
	s_addc_u32 s97, s15, 0
	global_load_dwordx4 v[188:191], v204, s[96:97]
	global_load_dwordx4 v[192:195], v204, s[96:97] offset:16
	global_load_dwordx4 v[196:199], v204, s[96:97] offset:32
	global_load_dwordx4 v[200:203], v204, s[96:97] offset:48
	v_mov_b32_e32 v205, 0x358637bd
	s_waitcnt vmcnt(0)
	v_add_f32_e32 v188, v188, v189
	v_add_f32_e32 v190, v190, v191
	v_add_f32_e32 v192, v192, v193
	v_add_f32_e32 v194, v194, v195
	v_add_f32_e32 v196, v196, v197
	v_add_f32_e32 v198, v198, v199
	v_add_f32_e32 v200, v200, v201
	v_add_f32_e32 v202, v202, v203
	v_add_f32_e32 v188, v188, v190
	v_add_f32_e32 v192, v192, v194
	v_add_f32_e32 v196, v196, v198
	v_add_f32_e32 v200, v200, v202
	v_add_f32_e32 v188, v188, v192
	v_add_f32_e32 v196, v196, v200
	v_add_f32_e32 v188, v188, v196
	s_nop 1
	v_add_f32_dpp v192, v188, v188 quad_perm:[1,0,3,2] row_mask:0xf bank_mask:0xf
	v_fmamk_f32 v192, v192, 0x3a000000, v205
	v_rsq_f32_e32 v192, v192
	s_lshl_b32 s96, s95, 7
	s_add_i32 s96, s96, 0x21000
	v_lshrrev_b32_e32 v204, 1, v220
	v_lshl_add_u32 v204, v204, 2, s96
	ds_write_b32 v204, v192
	s_mov_b32 s99, 2
	s_branch .LBB0_1145
